# P4 static priority raise for waves 0-3 instead of waves 4-7
# speedup vs baseline: 1.0046x; 1.0046x over previous
.LBB0_530:
	s_or_b64 exec, exec, s[0:1]
	v_readfirstlane_b32 s98, v222
	s_cmp_lt_u32 s98, 0x100
	s_cbranch_scc0 .Lprio_p4
	s_setprio 1
